# state tile S (f32, re-read only by its own workgroup) stored write-through (sc1) so it is not dirty in L2 at the P4|P5 grid barrier's write-back
# baseline (speedup 1.0000x reference)
;     __device__ __forceinline__ void operator()(const f32x4 (&acc)[2][2][4][2], const Unit& u, int wr, int wc, int fr, int fq) const {
;         const int row0 = u.pm * 256 + wr * 64 + fr;
; #pragma unroll
;         for (int ai = 0; ai < 2; ++ai)
; #pragma unroll
;             for (int m = 0; m < 4; ++m) {
;                 float* rp = S + ((size_t)u.g * NCH + row0 + ai * 128 + m * 16) * 256 + wc * 32 + 4 * fq;
; #pragma unroll
;                 for (int bj = 0; bj < 2; ++bj)
; #pragma unroll
;                     for (int n = 0; n < 2; ++n) *(f32x4*)(rp + bj * 128 + n * 16) = acc[ai][bj][m][n];
;             }
.LBB0_526:
	v_lshl_add_u32 v146, s7, 8, v142
	s_ashr_i32 s21, s20, 31
	v_ashrrev_i32_e32 v147, 31, v146
	s_lshl_b64 s[20:21], s[20:21], 19
	v_lshlrev_b64 v[146:147], 10, v[146:147]
	v_lshl_add_u64 v[146:147], v[146:147], 0, s[20:21]
	v_lshl_add_u64 v[148:149], s[16:17], 0, v[146:147]
	v_lshl_add_u64 v[148:149], v[148:149], 0, s[58:59]
	v_lshl_add_u64 v[148:149], v[148:149], 0, v[200:201]
	flat_store_dwordx4 v[148:149], v[124:127] sc1
	flat_store_dwordx4 v[148:149], v[120:123] offset:64 sc1
	flat_store_dwordx4 v[148:149], v[104:107] offset:512 sc1
	flat_store_dwordx4 v[148:149], v[96:99] offset:576 sc1
	s_mov_b64 s[20:21], 0x20000
	s_mov_b32 s1, 0x24000
	v_or_b32_e32 v96, 0x4000, v146
	v_mov_b32_e32 v97, v147
	v_lshl_add_u64 v[96:97], v[136:137], 0, v[96:97]
	flat_store_dwordx4 v[96:97], v[116:119] sc1
	flat_store_dwordx4 v[96:97], v[112:115] offset:64 sc1
	flat_store_dwordx4 v[96:97], v[88:91] offset:512 sc1
	flat_store_dwordx4 v[96:97], v[80:83] offset:576 sc1
	s_nop 1
	v_or_b32_e32 v80, 0x8000, v146
	v_mov_b32_e32 v81, v147
	v_lshl_add_u64 v[80:81], v[136:137], 0, v[80:81]
	v_or_b32_e32 v146, 0xc000, v146
	flat_store_dwordx4 v[80:81], v[108:111] sc1
	flat_store_dwordx4 v[80:81], v[100:103] offset:64 sc1
	flat_store_dwordx4 v[80:81], v[76:79] offset:512 sc1
	flat_store_dwordx4 v[80:81], v[72:75] offset:576 sc1
	s_nop 1
	v_lshl_add_u64 v[72:73], v[136:137], 0, v[146:147]
	flat_store_dwordx4 v[72:73], v[92:95] sc1
	flat_store_dwordx4 v[72:73], v[84:87] offset:64 sc1
	flat_store_dwordx4 v[72:73], v[68:71] offset:512 sc1
	flat_store_dwordx4 v[72:73], v[64:67] offset:576 sc1
	s_nop 1
	v_add_co_u32_e32 v66, vcc, s95, v148
	v_lshl_add_u64 v[64:65], v[148:149], 0, s[20:21]
	s_nop 0
	v_addc_co_u32_e32 v67, vcc, 0, v149, vcc
	flat_store_dwordx4 v[66:67], v[60:63] sc1
	flat_store_dwordx4 v[64:65], v[56:59] offset:64 sc1
	flat_store_dwordx4 v[64:65], v[44:47] offset:512 sc1
	flat_store_dwordx4 v[64:65], v[40:43] offset:576 sc1
	s_mov_b64 s[20:21], 0x24000
	s_nop 0
	v_add_co_u32_e32 v42, vcc, s1, v148
	s_mov_b32 s1, 0x28000
	s_nop 0
	v_addc_co_u32_e32 v43, vcc, 0, v149, vcc
	v_lshl_add_u64 v[40:41], v[148:149], 0, s[20:21]
	flat_store_dwordx4 v[42:43], v[52:55] sc1
	flat_store_dwordx4 v[40:41], v[48:51] offset:64 sc1
	flat_store_dwordx4 v[40:41], v[28:31] offset:512 sc1
	flat_store_dwordx4 v[40:41], v[24:27] offset:576 sc1
	s_mov_b64 s[20:21], 0x28000
	s_nop 0
	v_add_co_u32_e32 v26, vcc, s1, v148
	v_lshl_add_u64 v[24:25], v[148:149], 0, s[20:21]
	s_nop 0
	v_addc_co_u32_e32 v27, vcc, 0, v149, vcc
	flat_store_dwordx4 v[26:27], v[36:39] sc1
	flat_store_dwordx4 v[24:25], v[32:35] offset:64 sc1
	flat_store_dwordx4 v[24:25], v[12:15] offset:512 sc1
	flat_store_dwordx4 v[24:25], v[8:11] offset:576 sc1
	s_mov_b64 s[20:21], 0x2c000
	s_nop 0
	v_add_co_u32_e32 v10, vcc, 0x2c000, v148
	v_lshl_add_u64 v[8:9], v[148:149], 0, s[20:21]
	s_nop 0
	v_addc_co_u32_e32 v11, vcc, 0, v149, vcc
	s_and_b64 vcc, exec, s[38:39]
	s_mov_b64 s[20:21], -1
	flat_store_dwordx4 v[10:11], v[20:23] sc1
	flat_store_dwordx4 v[8:9], v[16:19] offset:64 sc1
	flat_store_dwordx4 v[8:9], v[4:7] offset:512 sc1
	flat_store_dwordx4 v[8:9], v[0:3] offset:576 sc1
	s_cbranch_vccnz .LBB0_517
	s_andn2_b64 vcc, exec, s[10:11]
	s_cbranch_vccnz .LBB0_516
	s_barrier
	s_branch .LBB0_516
